# static s_setprio 1 for waves 4-7 (younger half) through the token-mixer phases, on top of the stagger version
# speedup vs baseline: 1.0003x; 1.0003x over previous
; #define LAS __attribute__((address_space(3)))
; __device__ __forceinline__ KArgs kargs() { KArgs p = (KArgs)__builtin_amdgcn_kernarg_segment_ptr(); asm volatile("" : "+s"(p)); return p; }
; __global__ void __launch_bounds__(NTHR, 2) fwd_megakernel(Args A) {
;     ...
;         { KArgs P = kargs(); const bf16* Z = (const bf16*)WSP(WS_R); bf16* YC = (bf16*)WSP(WS_YC);
;           const int tid = threadIdx.x, lane = tid & 63, wave = __builtin_amdgcn_readfirstlane(tid >> 6);
;           const int vb = (G % 8 == 0) ? (int)(blockIdx.x % 8) * (G / 8) + (int)(blockIdx.x / 8) : (int)blockIdx.x;
;           const int gw = vb * NWAVES + wave, NGW = G * NWAVES;
;           LAS unsigned char* vt = lds + wave * WAVE_LDS;
;           if (layer == 0) {
;     ...
;             for (int t = gw; t < 2048; t += NGW) dil_task((const bf16*)WSP(WS_QKV), YC, P->in[11], P->in[12], vt, t, lane);
.LBB0_1486:
	s_or_b64 exec, exec, s[4:5]
	v_readlane_b32 s46, v253, 1
	v_readlane_b32 s47, v253, 2
	s_barrier
	v_readfirstlane_b32 vcc_lo, v218
	s_nop 4
	s_bfe_u32 vcc_lo, vcc_lo, 0x40006
	s_cmp_lt_u32 vcc_lo, 4
	s_cbranch_scc1 .Lstag_skip
	s_sleep 48
	s_setprio 1
